# v17: v16 + layer-1 FFN2 weight conversion moved into the idle CUs of layer-1 FFN1 last round; P0 of layer 1 has no conversion loop left
# speedup vs baseline: 1.0496x; 1.0020x over previous
; __device__ __forceinline__ void phase_prologue(PtrTab TB, unsigned char* ws, float* xout, int l, LAS unsigned char* lds, int gw, int NGW, int lane, int wave) {
;     ...
;     for (int it = gw; it < S14; it += NGW) {
.LBB0_23:
	s_cmpk_eq_u32 s8, 0x800
	s_cbranch_scc0 .Ltr_start
	s_cmpk_eq_u32 s94, 1
	s_cbranch_scc1 .LBB0_214

; #define g1 (tab_in(TB, 2) + l * D)
; #define gm (tab_in(TB, 5) + l * D)
; __device__ __forceinline__ void phase_prologue(PtrTab TB, unsigned char* ws, float* xout, int l, LAS unsigned char* lds, int gw, int NGW, int lane, int wave) {
;     ...
;     for (int it = gw; it < S14; it += NGW) {
;         if (it < S1 || (it >= S12 && it < S13)) {
;             const bool second = it >= S12; const int r = second ? it - S12 : it; const int kb = r / 88, nb = r % 88; const int n = nb * 64;
;             const int half = n >= DFF ? 1 : 0, nn = n - half * DFF; const int drow = (nn >> 7) * 256 + half * 128 + (nn & 127);
;             tr_item(second ? w2i : w1i, 2 * DFF, n, kb * 64, second ? g2 : g1, (bf16*)(ws + (second ? WS_W2IN : WS_W1IN)), D, drow, scr, lane);
;         } else if (it < S2 || it >= S13) {
;             const bool second = it >= S13; const int r = second ? it - S13 : it - S1; const int kb = r / 16, nb = r % 16;
;             tr_item(second ? w2o : w1o, D, nb * 64, kb * 64, nullptr, (bf16*)(ws + (second ? WS_W2OUT : WS_W1OUT)), DFF, nb * 64, scr, lane);
;         } else if (it < S3) { const int r = it - S2, kb = r / 64, nb = r % 64; tr_item(win, INW, nb * 64, kb * 64, gm, (bf16*)(ws + WS_WIN), D, nb * 64, scr, lane);
;         } else if (it < S4) { const int r = it - S3, kb = r / 48, nb = r % 48; tr_item(win, INW, 4104 + nb * 64, kb * 64, gm, (bf16*)(ws + WS_WG), D, nb * 64, scr, lane);
;         } else if (it < S5) { const int r = it - S4, kb = r / 16, nb = r % 16; tr_item(wub, D, nb * 64, kb * 64, nullptr, (bf16*)(ws + WS_UB), D, nb * 64, scr, lane);
;         } else if (it < S6) { const int r = it - S5, kb = r / 16, nb = r % 16; tr_item(wuc, D, nb * 64, kb * 64, nullptr, (bf16*)(ws + WS_UC), 512, nb * 64, scr, lane);
;         } else if (it < S8) { const bool xg = it >= S7; const int r = xg ? it - S7 : it - S6; const int hh = r >> 2, kb = (r >> 1) & 1, nb = r & 1;
;             tr_item((xg ? wrx : wra) + hh * 16384, 128, nb * 64, kb * 64, nullptr, (bf16*)(ws + (xg ? WS_WXT : WS_WAT)) + hh * 16384, 128, nb * 64, scr, lane);
;         } else if (it < S9) { const int r = it - S8, kb = r / 16, nb = r % 16; tr_item(wo, D, nb * 64, kb * 64, nullptr, (bf16*)(ws + WS_WO), D, nb * 64, scr, lane);
;         } else if (it < S10) { const int r = it - S9, kb = r / 16, nb = r % 16; tr_item(wxq, D, nb * 64, kb * 64, gc, (bf16*)(ws + WS_WXQ), D, nb * 64, scr, lane);
.LBB0_340:
	v_readlane_b32 s0, v254, 58
	v_readlane_b32 s1, v254, 0
	v_readlane_b32 s2, v254, 2
	s_nop 3
	s_cmp_eq_u32 s0, 0
	s_cbranch_scc1 .Lof2_skip
	s_cmpk_lg_u32 s1, 0x100
	s_cbranch_scc1 .Lof2_skip
	s_cmpk_lt_u32 s2, 0xa0
	s_cbranch_scc1 .Lof2_skip
	v_lshrrev_b32_e32 v50, 6, v197
	v_and_b32_e32 v49, 63, v197
	s_nop 0
	v_readfirstlane_b32 s3, v50
	s_nop 3
	s_sub_u32 s2, s2, 0xa0
	s_lshl_b32 s2, s2, 3
	s_add_u32 s12, s2, s3
	s_mul_i32 s5, s3, 0x4100
	v_and_b32_e32 v40, 15, v49
	v_lshlrev_b32_e32 v40, 2, v40
	v_lshrrev_b32_e32 v41, 4, v49
	v_and_b32_e32 v42, 7, v49
	v_lshlrev_b32_e32 v42, 3, v42
	v_lshrrev_b32_e32 v44, 3, v49
	v_mul_u32_u24_e32 v45, 0x104, v41
	v_lshl_add_u32 v45, v40, 2, v45
	v_add_u32_e32 v45, s5, v45
	v_mul_u32_u24_e32 v48, 0x104, v42
	v_lshl_add_u32 v48, v44, 2, v48
	v_add_u32_e32 v48, s5, v48
	s_addk_i32 s12, 0x1600
.Lof2_item:
	s_mov_b32 s0, s12
	s_cmpk_lt_u32 s0, 1408
	s_cbranch_scc1 .Lof2_seg0
	s_cmpk_lt_u32 s0, 2112
	s_cbranch_scc1 .Lof2_seg1
	s_cmpk_lt_u32 s0, 3136
	s_cbranch_scc1 .Lof2_seg2
	s_cmpk_lt_u32 s0, 3904
	s_cbranch_scc1 .Lof2_seg3
	s_cmpk_lt_u32 s0, 4160
	s_cbranch_scc1 .Lof2_seg4
	s_cmpk_lt_u32 s0, 4288
	s_cbranch_scc1 .Lof2_seg5
	s_cmpk_lt_u32 s0, 4320
	s_cbranch_scc1 .Lof2_seg6
	s_cmpk_lt_u32 s0, 4352
	s_cbranch_scc1 .Lof2_seg7
	s_cmpk_lt_u32 s0, 4608
	s_cbranch_scc1 .Lof2_seg8
	s_cmpk_lt_u32 s0, 4864
	s_cbranch_scc1 .Lof2_seg9
	s_cmpk_lt_u32 s0, 5376
	s_cbranch_scc1 .Lof2_seg10
	s_cmpk_lt_u32 s0, 5632
	s_cbranch_scc1 .Lof2_seg11
	s_cmpk_lt_u32 s0, 7040
	s_cbranch_scc1 .Lof2_seg12
	s_branch .Lof2_seg13

; #define g1 (tab_in(TB, 2) + l * D)
; #define w1i (tab_in(TB, 3) + (size_t)l * D * 2 * DFF)
; #define w1o (tab_in(TB, 4) + (size_t)l * DFF * D)
; __device__ __forceinline__ void phase_prologue(PtrTab TB, unsigned char* ws, float* xout, int l, LAS unsigned char* lds, int gw, int NGW, int lane, int wave) {
;     ...
;             const bool second = it >= S12; const int r = second ? it - S12 : it; const int kb = r / 88, nb = r % 88; const int n = nb * 64;
;             const int half = n >= DFF ? 1 : 0, nn = n - half * DFF; const int drow = (nn >> 7) * 256 + half * 128 + (nn & 127);
;             tr_item(second ? w2i : w1i, 2 * DFF, n, kb * 64, second ? g2 : g1, (bf16*)(ws + (second ? WS_W2IN : WS_W1IN)), D, drow, scr, lane);
;         } else if (it < S2 || it >= S13) {
;             const bool second = it >= S13; const int r = second ? it - S13 : it - S1; const int kb = r / 16, nb = r % 16;
;             tr_item(second ? w2o : w1o, D, nb * 64, kb * 64, nullptr, (bf16*)(ws + (second ? WS_W2OUT : WS_W1OUT)), DFF, nb * 64, scr, lane);
.Lof2_common:
	s_load_dwordx2 s[60:61], s[100:101], s6
	s_mov_b64 s[72:73], 0
	s_bitcmp1_b32 s34, 2
	s_cbranch_scc0 .Lof2_nogptr
	s_load_dwordx2 s[72:73], s[100:101], s21
.Lof2_nogptr:
	s_mul_i32 s31, s0, s5
	s_lshr_b32 s31, s31, 16
	s_mul_i32 s87, s31, s1
	s_sub_u32 s87, s0, s87
	s_lshl_b32 s4, s31, 6
	s_lshl_b32 s9, s87, 6
	s_add_u32 s20, s20, s9
	s_bitcmp1_b32 s34, 0
	s_cbranch_scc0 .Lof2_noswi
	s_cmp_ge_u32 s87, 44
	s_cselect_b32 s24, 1, 0
	s_mul_i32 s25, s24, 44
	s_sub_u32 s25, s87, s25
	s_lshr_b32 s9, s25, 1
	s_lshl_b32 s9, s9, 8
	s_lshl_b32 s24, s24, 7
	s_add_u32 s9, s9, s24
	s_and_b32 s25, s25, 1
	s_lshl_b32 s25, s25, 6
	s_add_u32 s9, s9, s25

; #define LAS __attribute__((address_space(3)))
; __device__ __forceinline__ unsigned pk2(float lo, float hi) { return f2bf(lo) | (f2bf(hi) << 16); }
; #define LDS_WAIT() asm volatile("s_waitcnt lgkmcnt(0)" ::: "memory")
; #define g1 (tab_in(TB, 2) + l * D)
; #define w1i (tab_in(TB, 3) + (size_t)l * D * 2 * DFF)
; #define w1o (tab_in(TB, 4) + (size_t)l * DFF * D)
; #define gm (tab_in(TB, 5) + l * D)
; #define win (tab_in(TB, 6) + (size_t)l * D * INW)
; __device__ __forceinline__ void tr_item(const float* W, int ldn, int col0, int k0, const float* g, bf16* WT, int ldk, int drow0, LAS float* scr, int lane) {
;     ...
;     for (int i = 0; i < 16; ++i) { const int kk = 4 * i + kr; f32x4 v = *(const f32x4*)(W + (size_t)(k0 + kk) * ldn + col0 + n4); if (g) v = v * g[k0 + kk];
;         LAS float* d = scr + kk * 65 + n4; d[0] = v.x; d[1] = v.y; d[2] = v.z; d[3] = v.w; }
;     LDS_WAIT(); asm volatile("" ::: "memory");
;     const int c = lane & 7;
; #pragma unroll
;     for (int j = 0; j < 8; ++j) { const int n = (lane >> 3) + 8 * j; const LAS float* s = scr + (8 * c) * 65 + n;
;         v4u o; o.x = pk2(s[0 * 65], s[1 * 65]); o.y = pk2(s[2 * 65], s[3 * 65]); o.z = pk2(s[4 * 65], s[5 * 65]); o.w = pk2(s[6 * 65], s[7 * 65]);
;         *(v4u*)(WT + (size_t)(drow0 + n) * ldk + k0 + 8 * c) = o; }
; __device__ __forceinline__ void phase_prologue(PtrTab TB, unsigned char* ws, float* xout, int l, LAS unsigned char* lds, int gw, int NGW, int lane, int wave) {
;     ...
;             const bool second = it >= S12; const int r = second ? it - S12 : it; const int kb = r / 88, nb = r % 88; const int n = nb * 64;
;             const int half = n >= DFF ? 1 : 0, nn = n - half * DFF; const int drow = (nn >> 7) * 256 + half * 128 + (nn & 127);
;             tr_item(second ? w2i : w1i, 2 * DFF, n, kb * 64, second ? g2 : g1, (bf16*)(ws + (second ? WS_W2IN : WS_W1IN)), D, drow, scr, lane);
;         } else if (it < S2 || it >= S13) {
;             const bool second = it >= S13; const int r = second ? it - S13 : it - S1; const int kb = r / 16, nb = r % 16;
;             tr_item(second ? w2o : w1o, D, nb * 64, kb * 64, nullptr, (bf16*)(ws + (second ? WS_W2OUT : WS_W1OUT)), DFF, nb * 64, scr, lane);
;         } else if (it < S3) { const int r = it - S2, kb = r / 64, nb = r % 64; tr_item(win, INW, nb * 64, kb * 64, gm, (bf16*)(ws + WS_WIN), D, nb * 64, scr, lane);
.Lof2_norg:
	s_mov_b32 s95, s13
	s_mul_i32 s97, s4, s18
	s_add_u32 s97, s97, s20
	s_lshl_b32 s97, s97, 2
	s_add_u32 s95, s95, s97
	s_lshl_b32 s38, s18, 4
	s_lshl_b32 s44, s32, 4
	s_mul_i32 s24, s9, s32
	s_add_u32 s24, s24, s4
	s_lshl_b32 s24, s24, 1
	s_add_u32 s24, s24, s23
	s_add_u32 s24, s82, s24
	s_addc_u32 s25, s83, 0
	s_movk_i32 s97, 0x1000
	s_lshl_b32 s1, s4, 2
	s_add_u32 s97, s97, s1
	v_mul_u32_u24_e32 v232, s18, v41
	v_add_lshl_u32 v232, v232, v40, 2
	v_lshlrev_b32_e32 v233, 2, v41
	v_mul_u32_u24_e32 v244, s32, v44
	v_add_lshl_u32 v244, v244, v42, 1
	v_add_u32_e32 v245, s44, v244
	v_add_u32_e32 v246, s44, v245
	v_add_u32_e32 v247, s44, v246
	v_add_u32_e32 v248, s44, v247
	v_add_u32_e32 v249, s44, v248
	v_add_u32_e32 v250, s44, v249
	v_add_u32_e32 v251, s44, v250
	v_mov_b32_e32 v242, v45
	v_add_u32_e32 v243, 0x400, v48
	s_waitcnt lgkmcnt(0)
	s_add_u32 s2, s60, s95
	s_addc_u32 s3, s61, 0
	s_add_u32 s98, s72, s97
	s_addc_u32 s99, s73, 0
	s_bitcmp1_b32 s34, 2
	s_cbranch_scc0 .Lof2_gone
	global_load_dword v210, v233, s[98:99] offset:0
	global_load_dword v211, v233, s[98:99] offset:16
	global_load_dword v212, v233, s[98:99] offset:32
	global_load_dword v213, v233, s[98:99] offset:48
	global_load_dword v214, v233, s[98:99] offset:64
	global_load_dword v215, v233, s[98:99] offset:80
	global_load_dword v216, v233, s[98:99] offset:96
	global_load_dword v217, v233, s[98:99] offset:112
	global_load_dword v218, v233, s[98:99] offset:128
	global_load_dword v219, v233, s[98:99] offset:144
	global_load_dword v220, v233, s[98:99] offset:160
	global_load_dword v221, v233, s[98:99] offset:176
	global_load_dword v222, v233, s[98:99] offset:192
	global_load_dword v223, v233, s[98:99] offset:208
	global_load_dword v230, v233, s[98:99] offset:224
	global_load_dword v231, v233, s[98:99] offset:240
	s_branch .Lof2_gdone

; #define LAS __attribute__((address_space(3)))
; __device__ __forceinline__ void tr_item(const float* W, int ldn, int col0, int k0, const float* g, bf16* WT, int ldk, int drow0, LAS float* scr, int lane) {
;     ...
;     for (int i = 0; i < 16; ++i) { const int kk = 4 * i + kr; f32x4 v = *(const f32x4*)(W + (size_t)(k0 + kk) * ldn + col0 + n4); if (g) v = v * g[k0 + kk];
;         LAS float* d = scr + kk * 65 + n4; d[0] = v.x; d[1] = v.y; d[2] = v.z; d[3] = v.w; }
.Lof2_gdone:
	global_load_dwordx4 v[146:149], v232, s[2:3] nt
	v_add_u32_e32 v232, s38, v232
	global_load_dwordx4 v[150:153], v232, s[2:3] nt
	v_add_u32_e32 v232, s38, v232
	global_load_dwordx4 v[154:157], v232, s[2:3] nt
	v_add_u32_e32 v232, s38, v232
	global_load_dwordx4 v[158:161], v232, s[2:3] nt
	v_add_u32_e32 v232, s38, v232
	global_load_dwordx4 v[166:169], v232, s[2:3] nt
	v_add_u32_e32 v232, s38, v232
	global_load_dwordx4 v[170:173], v232, s[2:3] nt
	v_add_u32_e32 v232, s38, v232
	global_load_dwordx4 v[174:177], v232, s[2:3] nt
	v_add_u32_e32 v232, s38, v232
	global_load_dwordx4 v[178:181], v232, s[2:3] nt
	v_add_u32_e32 v232, s38, v232
	global_load_dwordx4 v[182:185], v232, s[2:3] nt
	v_add_u32_e32 v232, s38, v232
	global_load_dwordx4 v[186:189], v232, s[2:3] nt
	v_add_u32_e32 v232, s38, v232
	global_load_dwordx4 v[190:193], v232, s[2:3] nt
	v_add_u32_e32 v232, s38, v232
	global_load_dwordx4 v[108:111], v232, s[2:3] nt
	v_add_u32_e32 v232, s38, v232
	global_load_dwordx4 v[112:115], v232, s[2:3] nt
	v_add_u32_e32 v232, s38, v232
	global_load_dwordx4 v[116:119], v232, s[2:3] nt
	v_add_u32_e32 v232, s38, v232
	global_load_dwordx4 v[120:123], v232, s[2:3] nt
	v_add_u32_e32 v232, s38, v232
	global_load_dwordx4 v[124:127], v232, s[2:3] nt
	s_waitcnt vmcnt(15)
	v_mul_f32_e32 v146, v210, v146
	v_mul_f32_e32 v147, v210, v147
	v_mul_f32_e32 v148, v210, v148
	v_mul_f32_e32 v149, v210, v149
	ds_write2_b32 v242, v146, v147 offset1:1
	ds_write2_b32 v242, v148, v149 offset0:2 offset1:3
	v_add_u32_e32 v242, 0x410, v242
	s_waitcnt vmcnt(14)
	v_mul_f32_e32 v150, v211, v150
	v_mul_f32_e32 v151, v211, v151
	v_mul_f32_e32 v152, v211, v152
	v_mul_f32_e32 v153, v211, v153
	ds_write2_b32 v242, v150, v151 offset1:1
	ds_write2_b32 v242, v152, v153 offset0:2 offset1:3
	v_add_u32_e32 v242, 0x410, v242
	s_waitcnt vmcnt(13)
	v_mul_f32_e32 v154, v212, v154
	v_mul_f32_e32 v155, v212, v155
	v_mul_f32_e32 v156, v212, v156
	v_mul_f32_e32 v157, v212, v157
	ds_write2_b32 v242, v154, v155 offset1:1
	ds_write2_b32 v242, v156, v157 offset0:2 offset1:3
	v_add_u32_e32 v242, 0x410, v242
	s_waitcnt vmcnt(12)
	v_mul_f32_e32 v158, v213, v158
	v_mul_f32_e32 v159, v213, v159
	v_mul_f32_e32 v160, v213, v160
	v_mul_f32_e32 v161, v213, v161
	ds_write2_b32 v242, v158, v159 offset1:1
	ds_write2_b32 v242, v160, v161 offset0:2 offset1:3
	v_add_u32_e32 v242, 0x410, v242
	s_waitcnt vmcnt(11)
	v_mul_f32_e32 v166, v214, v166
	v_mul_f32_e32 v167, v214, v167
	v_mul_f32_e32 v168, v214, v168
	v_mul_f32_e32 v169, v214, v169
	ds_write2_b32 v242, v166, v167 offset1:1
	ds_write2_b32 v242, v168, v169 offset0:2 offset1:3
	v_add_u32_e32 v242, 0x410, v242
	s_waitcnt vmcnt(10)
	v_mul_f32_e32 v170, v215, v170
	v_mul_f32_e32 v171, v215, v171
	v_mul_f32_e32 v172, v215, v172
	v_mul_f32_e32 v173, v215, v173
	ds_write2_b32 v242, v170, v171 offset1:1
	ds_write2_b32 v242, v172, v173 offset0:2 offset1:3
	v_add_u32_e32 v242, 0x410, v242
	s_waitcnt vmcnt(9)
	v_mul_f32_e32 v174, v216, v174
	v_mul_f32_e32 v175, v216, v175
	v_mul_f32_e32 v176, v216, v176
	v_mul_f32_e32 v177, v216, v177
	ds_write2_b32 v242, v174, v175 offset1:1
	ds_write2_b32 v242, v176, v177 offset0:2 offset1:3
	v_add_u32_e32 v242, 0x410, v242
	s_waitcnt vmcnt(8)
	v_mul_f32_e32 v178, v217, v178
	v_mul_f32_e32 v179, v217, v179
	v_mul_f32_e32 v180, v217, v180
	v_mul_f32_e32 v181, v217, v181
	ds_write2_b32 v242, v178, v179 offset1:1
	ds_write2_b32 v242, v180, v181 offset0:2 offset1:3
	v_add_u32_e32 v242, 0x410, v242
	s_waitcnt vmcnt(7)
	v_mul_f32_e32 v182, v218, v182
	v_mul_f32_e32 v183, v218, v183
	v_mul_f32_e32 v184, v218, v184
	v_mul_f32_e32 v185, v218, v185
	ds_write2_b32 v242, v182, v183 offset1:1
	ds_write2_b32 v242, v184, v185 offset0:2 offset1:3
	v_add_u32_e32 v242, 0x410, v242
	s_waitcnt vmcnt(6)
	v_mul_f32_e32 v186, v219, v186
	v_mul_f32_e32 v187, v219, v187
	v_mul_f32_e32 v188, v219, v188
	v_mul_f32_e32 v189, v219, v189
	ds_write2_b32 v242, v186, v187 offset1:1
	ds_write2_b32 v242, v188, v189 offset0:2 offset1:3
	v_add_u32_e32 v242, 0x410, v242
	s_waitcnt vmcnt(5)
	v_mul_f32_e32 v190, v220, v190
	v_mul_f32_e32 v191, v220, v191
	v_mul_f32_e32 v192, v220, v192
	v_mul_f32_e32 v193, v220, v193
	ds_write2_b32 v242, v190, v191 offset1:1
	ds_write2_b32 v242, v192, v193 offset0:2 offset1:3
	v_add_u32_e32 v242, 0x410, v242
	s_waitcnt vmcnt(4)
	v_mul_f32_e32 v108, v221, v108
	v_mul_f32_e32 v109, v221, v109
	v_mul_f32_e32 v110, v221, v110
	v_mul_f32_e32 v111, v221, v111
	ds_write2_b32 v242, v108, v109 offset1:1
	ds_write2_b32 v242, v110, v111 offset0:2 offset1:3
	v_add_u32_e32 v242, 0x410, v242
	s_waitcnt vmcnt(3)
; #define LAS __attribute__((address_space(3)))
; __device__ __forceinline__ unsigned pk2(float lo, float hi) { return f2bf(lo) | (f2bf(hi) << 16); }
; #define LDS_WAIT() asm volatile("s_waitcnt lgkmcnt(0)" ::: "memory")
; __device__ __forceinline__ void tr_item(const float* W, int ldn, int col0, int k0, const float* g, bf16* WT, int ldk, int drow0, LAS float* scr, int lane) {
;     ...
;     LDS_WAIT(); asm volatile("" ::: "memory");
;     const int c = lane & 7;
; #pragma unroll
;     for (int j = 0; j < 8; ++j) { const int n = (lane >> 3) + 8 * j; const LAS float* s = scr + (8 * c) * 65 + n;
;         v4u o; o.x = pk2(s[0 * 65], s[1 * 65]); o.y = pk2(s[2 * 65], s[3 * 65]); o.z = pk2(s[4 * 65], s[5 * 65]); o.w = pk2(s[6 * 65], s[7 * 65]);
;         *(v4u*)(WT + (size_t)(drow0 + n) * ldk + k0 + 8 * c) = o; }
	v_mul_f32_e32 v112, v222, v112
	v_mul_f32_e32 v113, v222, v113
	v_mul_f32_e32 v114, v222, v114
	v_mul_f32_e32 v115, v222, v115
	ds_write2_b32 v242, v112, v113 offset1:1
	ds_write2_b32 v242, v114, v115 offset0:2 offset1:3
	v_add_u32_e32 v242, 0x410, v242
	s_waitcnt vmcnt(2)
	v_mul_f32_e32 v116, v223, v116
	v_mul_f32_e32 v117, v223, v117
	v_mul_f32_e32 v118, v223, v118
	v_mul_f32_e32 v119, v223, v119
	ds_write2_b32 v242, v116, v117 offset1:1
	ds_write2_b32 v242, v118, v119 offset0:2 offset1:3
	v_add_u32_e32 v242, 0x410, v242
	s_waitcnt vmcnt(1)
	v_mul_f32_e32 v120, v230, v120
	v_mul_f32_e32 v121, v230, v121
	v_mul_f32_e32 v122, v230, v122
	v_mul_f32_e32 v123, v230, v123
	ds_write2_b32 v242, v120, v121 offset1:1
	ds_write2_b32 v242, v122, v123 offset0:2 offset1:3
	v_add_u32_e32 v242, 0x410, v242
	s_waitcnt vmcnt(0)
	v_mul_f32_e32 v124, v231, v124
	v_mul_f32_e32 v125, v231, v125
	v_mul_f32_e32 v126, v231, v126
	v_mul_f32_e32 v127, v231, v127
	ds_write2_b32 v242, v124, v125 offset1:1
	ds_write2_b32 v242, v126, v127 offset0:2 offset1:3
	s_waitcnt lgkmcnt(0)
	ds_read2_b32 v[146:147], v48 offset0:0 offset1:65
	ds_read2_b32 v[148:149], v48 offset0:130 offset1:195
	ds_read2_b32 v[150:151], v243 offset0:4 offset1:69
	ds_read2_b32 v[152:153], v243 offset0:134 offset1:199
	ds_read2_b32 v[154:155], v48 offset0:8 offset1:73
	ds_read2_b32 v[156:157], v48 offset0:138 offset1:203
	ds_read2_b32 v[158:159], v243 offset0:12 offset1:77
	ds_read2_b32 v[160:161], v243 offset0:142 offset1:207
	ds_read2_b32 v[166:167], v48 offset0:16 offset1:81
	ds_read2_b32 v[168:169], v48 offset0:146 offset1:211
	ds_read2_b32 v[170:171], v243 offset0:20 offset1:85
	ds_read2_b32 v[172:173], v243 offset0:150 offset1:215
	s_waitcnt lgkmcnt(8)
	v_cvt_pk_bf16_f32 v146, v146, v147
	v_cvt_pk_bf16_f32 v147, v148, v149
	v_cvt_pk_bf16_f32 v148, v150, v151
	v_cvt_pk_bf16_f32 v149, v152, v153
	global_store_dwordx4 v244, v[146:149], s[24:25]
	ds_read2_b32 v[174:175], v48 offset0:24 offset1:89
	ds_read2_b32 v[176:177], v48 offset0:154 offset1:219
	ds_read2_b32 v[178:179], v243 offset0:28 offset1:93
	ds_read2_b32 v[180:181], v243 offset0:158 offset1:223
	s_waitcnt lgkmcnt(8)
	v_cvt_pk_bf16_f32 v154, v154, v155
	v_cvt_pk_bf16_f32 v155, v156, v157
	v_cvt_pk_bf16_f32 v156, v158, v159
	v_cvt_pk_bf16_f32 v157, v160, v161
	global_store_dwordx4 v245, v[154:157], s[24:25]
	ds_read2_b32 v[182:183], v48 offset0:32 offset1:97
	ds_read2_b32 v[184:185], v48 offset0:162 offset1:227
	ds_read2_b32 v[186:187], v243 offset0:36 offset1:101
	ds_read2_b32 v[188:189], v243 offset0:166 offset1:231
	s_waitcnt lgkmcnt(8)
	v_cvt_pk_bf16_f32 v166, v166, v167
	v_cvt_pk_bf16_f32 v167, v168, v169
	v_cvt_pk_bf16_f32 v168, v170, v171
	v_cvt_pk_bf16_f32 v169, v172, v173
	global_store_dwordx4 v246, v[166:169], s[24:25]
	ds_read2_b32 v[108:109], v48 offset0:40 offset1:105
	ds_read2_b32 v[110:111], v48 offset0:170 offset1:235
	ds_read2_b32 v[112:113], v243 offset0:44 offset1:109
	ds_read2_b32 v[114:115], v243 offset0:174 offset1:239
	s_waitcnt lgkmcnt(8)
	v_cvt_pk_bf16_f32 v174, v174, v175
	v_cvt_pk_bf16_f32 v175, v176, v177
	v_cvt_pk_bf16_f32 v176, v178, v179
	v_cvt_pk_bf16_f32 v177, v180, v181
	global_store_dwordx4 v247, v[174:177], s[24:25]
	ds_read2_b32 v[116:117], v48 offset0:48 offset1:113
	ds_read2_b32 v[118:119], v48 offset0:178 offset1:243
	ds_read2_b32 v[120:121], v243 offset0:52 offset1:117
	ds_read2_b32 v[122:123], v243 offset0:182 offset1:247
	s_waitcnt lgkmcnt(8)
	v_cvt_pk_bf16_f32 v182, v182, v183
	v_cvt_pk_bf16_f32 v183, v184, v185
	v_cvt_pk_bf16_f32 v184, v186, v187
	v_cvt_pk_bf16_f32 v185, v188, v189
	global_store_dwordx4 v248, v[182:185], s[24:25]
	ds_read2_b32 v[124:125], v48 offset0:56 offset1:121
	ds_read2_b32 v[126:127], v48 offset0:186 offset1:251
	ds_read2_b32 v[128:129], v243 offset0:60 offset1:125
	ds_read2_b32 v[130:131], v243 offset0:190 offset1:255
	s_waitcnt lgkmcnt(8)
	v_cvt_pk_bf16_f32 v108, v108, v109
	v_cvt_pk_bf16_f32 v109, v110, v111
	v_cvt_pk_bf16_f32 v110, v112, v113
	v_cvt_pk_bf16_f32 v111, v114, v115
	global_store_dwordx4 v249, v[108:111], s[24:25]
	s_waitcnt lgkmcnt(4)
	v_cvt_pk_bf16_f32 v116, v116, v117
	v_cvt_pk_bf16_f32 v117, v118, v119
	v_cvt_pk_bf16_f32 v118, v120, v121
	v_cvt_pk_bf16_f32 v119, v122, v123
	global_store_dwordx4 v250, v[116:119], s[24:25]
	s_waitcnt lgkmcnt(0)
	v_cvt_pk_bf16_f32 v124, v124, v125
	v_cvt_pk_bf16_f32 v125, v126, v127
	v_cvt_pk_bf16_f32 v126, v128, v129
	v_cvt_pk_bf16_f32 v127, v130, v131
	global_store_dwordx4 v251, v[124:127], s[24:25]
	s_addk_i32 s12, 0x300
	s_cmpk_lt_u32 s12, 0x1e40
	s_cbranch_scc1 .Lof2_item
